# P3 gate-column tile units: waves whose accumulators are never read (wc != 0) skip their MFMAs
# speedup vs baseline: 1.0027x; 1.0027x over previous
; #define PG8_STAGE(bufoff, gbase, voff) do { _Pragma("unroll") for (int _i = 0; _i < 2; ++_i) \
;         __builtin_amdgcn_global_load_lds((const unsigned*)((const char*)(gbase) + (voff)[_i]), (PG8_LAS unsigned*)(lds + (bufoff) + ldsw + _i * 8192), 16, 0, 0); } while (0)
; #define PG8_LDA(dst, b, h) do { _Pragma("unroll") for (int m = 0; m < 4; ++m) _Pragma("unroll") for (int k = 0; k < 2; ++k) dst[m][k] = *(const PG8_LAS bf16x8*)(lds + PG8_SA(b, h) + aoff + m * 2048 + k * 1024); } while (0)
; #define PG8_LDB(dst, b, h) do { _Pragma("unroll") for (int n = 0; n < 2; ++n) _Pragma("unroll") for (int k = 0; k < 2; ++k) dst[n][k] = *(const PG8_LAS bf16x8*)(lds + PG8_SB(b, h) + boff + n * 2048 + k * 1024); } while (0)
; #define PG8_MMA(ai, bj, At, Bt) do { __builtin_amdgcn_s_setprio(1); _Pragma("unroll") for (int m = 0; m < 4; ++m) _Pragma("unroll") for (int n = 0; n < 2; ++n) _Pragma("unroll") for (int k = 0; k < 2; ++k) \
;         acc[ai][bj][m][n] = __builtin_amdgcn_mfma_f32_16x16x32_bf16(Bt[n][k], At[m][k], acc[ai][bj][m][n], 0, 0, 0); __builtin_amdgcn_s_setprio(0); } while (0)
;     __device__ __forceinline__ void operator()(const f32x4 (&acc)[2][2][4][2], const Unit& u, int wr, int wc, int fr, int fq) const {
;     ...
;         } else if (wc == 0 && fq == 0) {
;             const f32x4 b0 = *(const f32x4*)bg, b1 = *(const f32x4*)(bg + 4);
; #pragma unroll
;             for (int ai = 0; ai < 2; ++ai)
; #pragma unroll
;                 for (int m = 0; m < 4; ++m) {
;                     const int row = row0 + ai * HALF + m * 16; const float r = tab ? rtab[row - u.pm * BM] : row_rstd(ss, row);
;                     *(f32x4*)(gates + (size_t)row * 8) = acc[ai][0][m][0] * r + b0;
;                     *(f32x4*)(gates + (size_t)row * 8 + 4) = acc[ai][0][m][1] * r + b1;
;                 }
; template <class Epi, class Sched, bool ALIGN_EPI = false, bool SP2 = false>
; __device__ __forceinline__ void gemm_phase(PG8_LAS unsigned char* lds, const Gemm g, const Sched& S, const Epi& E) {
;     ...
;             PG8_LDB(B0, 0, 0); PG8_LDB(B1, 0, 1); PG8_SCHED; PG8_LDA(At, 0, 0); PG8_STAGE(PG8_SA(1, 1), a1 + hstep, voffA);
;             PG8_WAIT_V(8); PG8_WAIT_L(0); PG8_BAR; PG8_MMA(0, 0, At, B0); PG8_MMA(0, 1, At, B1); PG8_BAR; PG8_SCHED;
;             PG8_LDA(At, 0, 1); PG8_STAGE(PG8_SB(0, 0), b2, voffB); PG8_STAGE(PG8_SB(0, 1), b2 + hstep, voffB); PG8_STAGE(PG8_SA(0, 0), a2, voffA);
.LBB0_463:
	v_readfirstlane_b32 s98, v152
	s_nop 3
	s_bfe_u32 s98, s98, 0x20006
	s_cmp_gt_i32 s28, 9
	s_cselect_b32 s98, s98, 0
	s_ashr_i32 s21, s20, 31
	s_lshl_b64 s[24:25], s[20:21], 19
	s_add_u32 s24, s76, s24
	s_addc_u32 s25, s77, s25
	s_and_b64 s[26:27], s[10:11], exec
	s_cselect_b32 s13, s25, s1
	s_cselect_b32 s21, s24, s0
	s_ashr_i32 s19, s18, 31
	s_lshl_b64 s[26:27], s[18:19], 19
	s_add_u32 s26, s33, s26
	s_addc_u32 s27, s36, s27
	s_and_b64 s[34:35], s[10:11], exec
	s_cselect_b32 s19, s27, s31
	s_cselect_b32 s58, s26, s30
	s_add_u32 s0, s0, 0x40080
	s_addc_u32 s1, s1, 0
	s_add_u32 s59, s30, 0x100
	s_addc_u32 s80, s31, 0
	s_mov_b32 s81, -2
	ds_read_b128 v[128:131], v149
	ds_read_b128 v[132:135], v149 offset:1024
	ds_read_b128 v[140:143], v149 offset:2048
	ds_read_b128 v[176:179], v149 offset:3072
	ds_read_b128 v[180:183], v150
	ds_read_b128 v[184:187], v150 offset:1024
	ds_read_b128 v[188:191], v150 offset:2048
	ds_read_b128 v[192:195], v150 offset:3072
	s_add_u32 s30, s0, 0xfffc0080
	s_addc_u32 s31, s1, -1
	s_cmp_eq_u32 s81, 12
	s_cselect_b32 s35, s13, s31
	s_cselect_b32 s34, s21, s30
	s_cselect_b32 s31, s19, s80
	s_cselect_b32 s30, s58, s59
	v_lshl_add_u64 v[228:229], s[0:1], 0, v[136:137]
	s_add_i32 m0, s29, 0xc000
	ds_read_b128 v[196:199], v151
	ds_read_b128 v[200:203], v151 offset:1024
	ds_read_b128 v[204:207], v151 offset:2048
	ds_read_b128 v[208:211], v151 offset:3072
	ds_read_b128 v[212:215], v151 offset:4096
	ds_read_b128 v[216:219], v151 offset:5120
	ds_read_b128 v[220:223], v151 offset:6144
	ds_read_b128 v[224:227], v151 offset:7168
	global_load_lds_dwordx4 v[228:229], off
	v_lshl_add_u64 v[228:229], s[0:1], 0, v[138:139]
	s_add_i32 m0, s29, 0xe000
	s_nop 0
	global_load_lds_dwordx4 v[228:229], off
	s_waitcnt vmcnt(8)
	s_waitcnt lgkmcnt(0)
	s_cmp_lg_u32 s98, 0
	s_setprio 1
	s_barrier
	s_cbranch_scc1 .Lgs_0
	v_mfma_f32_16x16x32_bf16 v[124:127], v[128:131], v[196:199], 0
	v_mfma_f32_16x16x32_bf16 v[120:123], v[140:143], v[196:199], 0
	v_mfma_f32_16x16x32_bf16 v[108:111], v[128:131], v[204:207], 0
	v_mfma_f32_16x16x32_bf16 v[104:107], v[140:143], v[204:207], 0
	v_mfma_f32_16x16x32_bf16 v[92:95], v[128:131], v[212:215], 0
	v_mfma_f32_16x16x32_bf16 v[88:91], v[140:143], v[212:215], 0
	v_mfma_f32_16x16x32_bf16 v[76:79], v[128:131], v[220:223], 0
	v_mfma_f32_16x16x32_bf16 v[72:75], v[140:143], v[220:223], 0
	v_mfma_f32_16x16x32_bf16 v[124:127], v[132:135], v[200:203], v[124:127]
	v_mfma_f32_16x16x32_bf16 v[120:123], v[176:179], v[200:203], v[120:123]
	v_mfma_f32_16x16x32_bf16 v[108:111], v[132:135], v[208:211], v[108:111]
	v_mfma_f32_16x16x32_bf16 v[104:107], v[176:179], v[208:211], v[104:107]
	v_mfma_f32_16x16x32_bf16 v[92:95], v[132:135], v[216:219], v[92:95]
	v_mfma_f32_16x16x32_bf16 v[88:91], v[176:179], v[216:219], v[88:91]
	v_mfma_f32_16x16x32_bf16 v[76:79], v[132:135], v[224:227], v[76:79]
	v_mfma_f32_16x16x32_bf16 v[72:75], v[176:179], v[224:227], v[72:75]
	s_setprio 0
	s_setprio 1
	v_mfma_f32_16x16x32_bf16 v[116:119], v[180:183], v[196:199], 0
	v_mfma_f32_16x16x32_bf16 v[112:115], v[188:191], v[196:199], 0
	v_mfma_f32_16x16x32_bf16 v[100:103], v[180:183], v[204:207], 0
	v_mfma_f32_16x16x32_bf16 v[96:99], v[188:191], v[204:207], 0
	v_mfma_f32_16x16x32_bf16 v[84:87], v[180:183], v[212:215], 0
	v_mfma_f32_16x16x32_bf16 v[80:83], v[188:191], v[212:215], 0
	v_mfma_f32_16x16x32_bf16 v[68:71], v[180:183], v[220:223], 0
	v_mfma_f32_16x16x32_bf16 v[64:67], v[188:191], v[220:223], 0
	v_mfma_f32_16x16x32_bf16 v[116:119], v[184:187], v[200:203], v[116:119]
	v_mfma_f32_16x16x32_bf16 v[112:115], v[192:195], v[200:203], v[112:115]
	v_mfma_f32_16x16x32_bf16 v[100:103], v[184:187], v[208:211], v[100:103]
	v_mfma_f32_16x16x32_bf16 v[96:99], v[192:195], v[208:211], v[96:99]
	v_mfma_f32_16x16x32_bf16 v[84:87], v[184:187], v[216:219], v[84:87]
	v_mfma_f32_16x16x32_bf16 v[80:83], v[192:195], v[216:219], v[80:83]
	v_mfma_f32_16x16x32_bf16 v[68:71], v[184:187], v[224:227], v[68:71]
	v_mfma_f32_16x16x32_bf16 v[64:67], v[192:195], v[224:227], v[64:67]
.Lgs_0:
	s_barrier
	s_setprio 0
	s_add_i32 s82, s46, s3
	v_lshl_add_u64 v[228:229], s[30:31], 0, v[158:159]
	s_mov_b32 m0, s82
	ds_read_b128 v[196:199], v151 offset:16384
	ds_read_b128 v[200:203], v151 offset:17408
	ds_read_b128 v[204:207], v151 offset:18432
	ds_read_b128 v[208:211], v151 offset:19456
	ds_read_b128 v[212:215], v151 offset:20480
	ds_read_b128 v[216:219], v151 offset:21504
	ds_read_b128 v[220:223], v151 offset:22528
	ds_read_b128 v[224:227], v151 offset:23552
	global_load_lds_dwordx4 v[228:229], off
	s_add_i32 m0, s82, 0x2000
	s_add_u32 s82, s30, 0x40000
	v_lshl_add_u64 v[248:249], s[30:31], 0, v[162:163]
	s_addc_u32 s83, s31, 0
	s_add_i32 s84, s47, s3
	global_load_lds_dwordx4 v[248:249], off
	v_lshl_add_u64 v[250:251], s[82:83], 0, v[158:159]
	s_mov_b32 m0, s84
	v_lshl_add_u64 v[252:253], s[34:35], 0, v[160:161]
	global_load_lds_dwordx4 v[250:251], off
	v_lshl_add_u64 v[250:251], s[82:83], 0, v[162:163]
	s_add_i32 m0, s84, 0x2000
	s_nop 0
	global_load_lds_dwordx4 v[250:251], off
	v_lshl_add_u64 v[250:251], s[34:35], 0, v[156:157]
	s_mov_b32 m0, s29
	s_nop 0
	global_load_lds_dwordx4 v[250:251], off
	s_mov_b32 m0, s37
	s_nop 0
	global_load_lds_dwordx4 v[252:253], off
	s_waitcnt vmcnt(8)
	s_waitcnt lgkmcnt(0)
	s_cmp_lg_u32 s98, 0
	s_setprio 1
	s_barrier
	s_cbranch_scc1 .Lgs_1
; #define PG8_STAGE(bufoff, gbase, voff) do { _Pragma("unroll") for (int _i = 0; _i < 2; ++_i) \
;         __builtin_amdgcn_global_load_lds((const unsigned*)((const char*)(gbase) + (voff)[_i]), (PG8_LAS unsigned*)(lds + (bufoff) + ldsw + _i * 8192), 16, 0, 0); } while (0)
; #define PG8_LDA(dst, b, h) do { _Pragma("unroll") for (int m = 0; m < 4; ++m) _Pragma("unroll") for (int k = 0; k < 2; ++k) dst[m][k] = *(const PG8_LAS bf16x8*)(lds + PG8_SA(b, h) + aoff + m * 2048 + k * 1024); } while (0)
; #define PG8_LDB(dst, b, h) do { _Pragma("unroll") for (int n = 0; n < 2; ++n) _Pragma("unroll") for (int k = 0; k < 2; ++k) dst[n][k] = *(const PG8_LAS bf16x8*)(lds + PG8_SB(b, h) + boff + n * 2048 + k * 1024); } while (0)
; #define PG8_MMA(ai, bj, At, Bt) do { __builtin_amdgcn_s_setprio(1); _Pragma("unroll") for (int m = 0; m < 4; ++m) _Pragma("unroll") for (int n = 0; n < 2; ++n) _Pragma("unroll") for (int k = 0; k < 2; ++k) \
;         acc[ai][bj][m][n] = __builtin_amdgcn_mfma_f32_16x16x32_bf16(Bt[n][k], At[m][k], acc[ai][bj][m][n], 0, 0, 0); __builtin_amdgcn_s_setprio(0); } while (0)
; #define PG8_WAIT_V(n) asm volatile("s_waitcnt vmcnt(" #n ")" ::: "memory")
; #define PG8_WAIT_L(n) asm volatile("s_waitcnt lgkmcnt(" #n ")" ::: "memory")
; #define PG8_BAR __builtin_amdgcn_s_barrier()
; #define PG8_SCHED __builtin_amdgcn_sched_barrier(0)
; template <class Epi, class Sched, bool ALIGN_EPI = false, bool SP2 = false>
; __device__ __forceinline__ void gemm_phase(PG8_LAS unsigned char* lds, const Gemm g, const Sched& S, const Epi& E) {
;     ...
;             PG8_WAIT_V(8); PG8_WAIT_L(0); PG8_BAR; PG8_MMA(1, 0, At, B0); PG8_MMA(1, 1, At, B1); PG8_BAR; PG8_SCHED;
;             PG8_LDB(B0, 1, 0); PG8_LDB(B1, 1, 1); PG8_SCHED; PG8_LDA(At, 1, 0); PG8_STAGE(PG8_SA(0, 1), a2 + hstep, voffA);
;             PG8_WAIT_V(8); PG8_WAIT_L(0); PG8_BAR; PG8_MMA(0, 0, At, B0); PG8_MMA(0, 1, At, B1); PG8_BAR; PG8_SCHED;
	v_mfma_f32_16x16x32_bf16 v[60:63], v[128:131], v[196:199], 0
	v_mfma_f32_16x16x32_bf16 v[56:59], v[140:143], v[196:199], 0
	v_mfma_f32_16x16x32_bf16 v[44:47], v[128:131], v[204:207], 0
	v_mfma_f32_16x16x32_bf16 v[40:43], v[140:143], v[204:207], 0
	v_mfma_f32_16x16x32_bf16 v[28:31], v[128:131], v[212:215], 0
	v_mfma_f32_16x16x32_bf16 v[24:27], v[140:143], v[212:215], 0
	v_mfma_f32_16x16x32_bf16 v[12:15], v[128:131], v[220:223], 0
	v_mfma_f32_16x16x32_bf16 v[8:11], v[140:143], v[220:223], 0
	v_mfma_f32_16x16x32_bf16 v[60:63], v[132:135], v[200:203], v[60:63]
	v_mfma_f32_16x16x32_bf16 v[56:59], v[176:179], v[200:203], v[56:59]
	v_mfma_f32_16x16x32_bf16 v[44:47], v[132:135], v[208:211], v[44:47]
	v_mfma_f32_16x16x32_bf16 v[40:43], v[176:179], v[208:211], v[40:43]
	v_mfma_f32_16x16x32_bf16 v[28:31], v[132:135], v[216:219], v[28:31]
	v_mfma_f32_16x16x32_bf16 v[24:27], v[176:179], v[216:219], v[24:27]
	v_mfma_f32_16x16x32_bf16 v[12:15], v[132:135], v[224:227], v[12:15]
	v_mfma_f32_16x16x32_bf16 v[8:11], v[176:179], v[224:227], v[8:11]
	s_setprio 0
	s_setprio 1
	v_mfma_f32_16x16x32_bf16 v[52:55], v[180:183], v[196:199], 0
	v_mfma_f32_16x16x32_bf16 v[48:51], v[188:191], v[196:199], 0
	v_mfma_f32_16x16x32_bf16 v[36:39], v[180:183], v[204:207], 0
	v_mfma_f32_16x16x32_bf16 v[32:35], v[188:191], v[204:207], 0
	v_mfma_f32_16x16x32_bf16 v[20:23], v[180:183], v[212:215], 0
	v_mfma_f32_16x16x32_bf16 v[16:19], v[188:191], v[212:215], 0
	v_mfma_f32_16x16x32_bf16 v[4:7], v[180:183], v[220:223], 0
	v_mfma_f32_16x16x32_bf16 v[0:3], v[188:191], v[220:223], 0
	v_mfma_f32_16x16x32_bf16 v[52:55], v[184:187], v[200:203], v[52:55]
	v_mfma_f32_16x16x32_bf16 v[48:51], v[192:195], v[200:203], v[48:51]
	v_mfma_f32_16x16x32_bf16 v[36:39], v[184:187], v[208:211], v[36:39]
	v_mfma_f32_16x16x32_bf16 v[32:35], v[192:195], v[208:211], v[32:35]
	v_mfma_f32_16x16x32_bf16 v[20:23], v[184:187], v[216:219], v[20:23]
	v_mfma_f32_16x16x32_bf16 v[16:19], v[192:195], v[216:219], v[16:19]
	v_mfma_f32_16x16x32_bf16 v[4:7], v[184:187], v[224:227], v[4:7]
	v_mfma_f32_16x16x32_bf16 v[0:3], v[192:195], v[224:227], v[0:3]
.Lgs_1:
	s_barrier
	s_setprio 0
	s_add_i32 s82, 0, 0x18000
	v_add_u32_e32 v144, s82, v146
	s_add_i32 s83, 0, 0x1c000
	ds_read_b128 v[128:131], v144
	ds_read_b128 v[132:135], v144 offset:1024
	ds_read_b128 v[140:143], v144 offset:2048
	ds_read_b128 v[176:179], v144 offset:3072
	v_add_u32_e32 v144, s83, v146
	ds_read_b128 v[180:183], v144
	ds_read_b128 v[184:187], v144 offset:1024
	ds_read_b128 v[188:191], v144 offset:2048
	ds_read_b128 v[192:195], v144 offset:3072
	s_add_u32 s34, s34, 0x40000
	s_addc_u32 s35, s35, 0
	s_mov_b32 m0, s38
	v_lshl_add_u64 v[238:239], s[34:35], 0, v[156:157]
	ds_read_b128 v[196:199], v151 offset:32768
	ds_read_b128 v[200:203], v151 offset:33792
	ds_read_b128 v[204:207], v151 offset:34816
	ds_read_b128 v[208:211], v151 offset:35840
	ds_read_b128 v[212:215], v151 offset:36864
	ds_read_b128 v[216:219], v151 offset:37888
	ds_read_b128 v[220:223], v151 offset:38912
	ds_read_b128 v[224:227], v151 offset:39936
	global_load_lds_dwordx4 v[238:239], off
	v_lshl_add_u64 v[238:239], s[34:35], 0, v[160:161]
	s_mov_b32 m0, s39
	s_nop 0
	global_load_lds_dwordx4 v[238:239], off
	s_waitcnt vmcnt(8)
	s_waitcnt lgkmcnt(0)
	s_cmp_lg_u32 s98, 0
	s_setprio 1
	s_barrier
	s_cbranch_scc1 .Lgs_2
	v_mfma_f32_16x16x32_bf16 v[124:127], v[128:131], v[196:199], v[124:127]
	v_mfma_f32_16x16x32_bf16 v[120:123], v[140:143], v[196:199], v[120:123]
	v_mfma_f32_16x16x32_bf16 v[108:111], v[128:131], v[204:207], v[108:111]
	v_mfma_f32_16x16x32_bf16 v[104:107], v[140:143], v[204:207], v[104:107]
	v_mfma_f32_16x16x32_bf16 v[92:95], v[128:131], v[212:215], v[92:95]
	v_mfma_f32_16x16x32_bf16 v[88:91], v[140:143], v[212:215], v[88:91]
	v_mfma_f32_16x16x32_bf16 v[76:79], v[128:131], v[220:223], v[76:79]
	v_mfma_f32_16x16x32_bf16 v[72:75], v[140:143], v[220:223], v[72:75]
	v_mfma_f32_16x16x32_bf16 v[124:127], v[132:135], v[200:203], v[124:127]
	v_mfma_f32_16x16x32_bf16 v[120:123], v[176:179], v[200:203], v[120:123]
	v_mfma_f32_16x16x32_bf16 v[108:111], v[132:135], v[208:211], v[108:111]
	v_mfma_f32_16x16x32_bf16 v[104:107], v[176:179], v[208:211], v[104:107]
	v_mfma_f32_16x16x32_bf16 v[92:95], v[132:135], v[216:219], v[92:95]
	v_mfma_f32_16x16x32_bf16 v[88:91], v[176:179], v[216:219], v[88:91]
	v_mfma_f32_16x16x32_bf16 v[76:79], v[132:135], v[224:227], v[76:79]
	v_mfma_f32_16x16x32_bf16 v[72:75], v[176:179], v[224:227], v[72:75]
	s_setprio 0
	s_setprio 1
	v_mfma_f32_16x16x32_bf16 v[116:119], v[180:183], v[196:199], v[116:119]
	v_mfma_f32_16x16x32_bf16 v[112:115], v[188:191], v[196:199], v[112:115]
	v_mfma_f32_16x16x32_bf16 v[100:103], v[180:183], v[204:207], v[100:103]
	v_mfma_f32_16x16x32_bf16 v[96:99], v[188:191], v[204:207], v[96:99]
	v_mfma_f32_16x16x32_bf16 v[84:87], v[180:183], v[212:215], v[84:87]
	v_mfma_f32_16x16x32_bf16 v[80:83], v[188:191], v[212:215], v[80:83]
	v_mfma_f32_16x16x32_bf16 v[68:71], v[180:183], v[220:223], v[68:71]
	v_mfma_f32_16x16x32_bf16 v[64:67], v[188:191], v[220:223], v[64:67]
	v_mfma_f32_16x16x32_bf16 v[116:119], v[184:187], v[200:203], v[116:119]
	v_mfma_f32_16x16x32_bf16 v[112:115], v[192:195], v[200:203], v[112:115]
	v_mfma_f32_16x16x32_bf16 v[100:103], v[184:187], v[208:211], v[100:103]
	v_mfma_f32_16x16x32_bf16 v[96:99], v[192:195], v[208:211], v[96:99]
	v_mfma_f32_16x16x32_bf16 v[84:87], v[184:187], v[216:219], v[84:87]
	v_mfma_f32_16x16x32_bf16 v[80:83], v[192:195], v[216:219], v[80:83]
	v_mfma_f32_16x16x32_bf16 v[68:71], v[184:187], v[224:227], v[68:71]
	v_mfma_f32_16x16x32_bf16 v[64:67], v[192:195], v[224:227], v[64:67]
; #define PG8_STAGE(bufoff, gbase, voff) do { _Pragma("unroll") for (int _i = 0; _i < 2; ++_i) \
;         __builtin_amdgcn_global_load_lds((const unsigned*)((const char*)(gbase) + (voff)[_i]), (PG8_LAS unsigned*)(lds + (bufoff) + ldsw + _i * 8192), 16, 0, 0); } while (0)
; #define PG8_LDA(dst, b, h) do { _Pragma("unroll") for (int m = 0; m < 4; ++m) _Pragma("unroll") for (int k = 0; k < 2; ++k) dst[m][k] = *(const PG8_LAS bf16x8*)(lds + PG8_SA(b, h) + aoff + m * 2048 + k * 1024); } while (0)
; #define PG8_MMA(ai, bj, At, Bt) do { __builtin_amdgcn_s_setprio(1); _Pragma("unroll") for (int m = 0; m < 4; ++m) _Pragma("unroll") for (int n = 0; n < 2; ++n) _Pragma("unroll") for (int k = 0; k < 2; ++k) \
;         acc[ai][bj][m][n] = __builtin_amdgcn_mfma_f32_16x16x32_bf16(Bt[n][k], At[m][k], acc[ai][bj][m][n], 0, 0, 0); __builtin_amdgcn_s_setprio(0); } while (0)
; #define PG8_WAIT_V(n) asm volatile("s_waitcnt vmcnt(" #n ")" ::: "memory")
; #define PG8_WAIT_L(n) asm volatile("s_waitcnt lgkmcnt(" #n ")" ::: "memory")
; #define PG8_BAR __builtin_amdgcn_s_barrier()
; #define PG8_SCHED __builtin_amdgcn_sched_barrier(0)
; template <class Epi, class Sched, bool ALIGN_EPI = false, bool SP2 = false>
; __device__ __forceinline__ void gemm_phase(PG8_LAS unsigned char* lds, const Gemm g, const Sched& S, const Epi& E) {
;     ...
;         for (int t = 0; t < nt; t += 2) {
;             const bool last = (t == nt - 2);
;             const char* a1 = cA + (size_t)(t + 1) * kstep;
;             const char* a2 = last ? nA : cA + (size_t)(t + 2) * kstep; const char* b2 = last ? nB : cB + (size_t)(t + 2) * kstep;
;             const char* a3 = a2 + kstep; const char* b3 = b2 + kstep;
;     ...
;             PG8_LDA(At, 1, 1); PG8_STAGE(PG8_SB(1, 0), b3, voffB); PG8_STAGE(PG8_SB(1, 1), b3 + hstep, voffB); PG8_STAGE(PG8_SA(1, 0), a3, voffA);
;             PG8_WAIT_V(8); PG8_WAIT_L(0); PG8_BAR; PG8_MMA(1, 0, At, B0); PG8_MMA(1, 1, At, B1); PG8_BAR; PG8_SCHED;
.Lgs_2:
	s_barrier
	s_setprio 0
	s_add_i32 s34, s82, s3
	v_lshl_add_u64 v[228:229], v[228:229], 0, s[6:7]
	s_mov_b32 m0, s34
	ds_read_b128 v[196:199], v151 offset:49152
	ds_read_b128 v[200:203], v151 offset:50176
	ds_read_b128 v[204:207], v151 offset:51200
	ds_read_b128 v[208:211], v151 offset:52224
	ds_read_b128 v[212:215], v151 offset:53248
	ds_read_b128 v[216:219], v151 offset:54272
	ds_read_b128 v[220:223], v151 offset:55296
	ds_read_b128 v[224:227], v151 offset:56320
	global_load_lds_dwordx4 v[228:229], off
	s_add_i32 m0, s34, 0x2000
	s_add_u32 s30, s30, 0x40080
	v_lshl_add_u64 v[228:229], v[248:249], 0, s[6:7]
	s_addc_u32 s31, s31, 0
	s_add_i32 s34, s83, s3
	global_load_lds_dwordx4 v[228:229], off
	v_lshl_add_u64 v[228:229], s[30:31], 0, v[158:159]
	s_mov_b32 m0, s34
	s_nop 0
	global_load_lds_dwordx4 v[228:229], off
	v_lshl_add_u64 v[228:229], s[30:31], 0, v[162:163]
	s_add_i32 m0, s34, 0x2000
	s_nop 0
	global_load_lds_dwordx4 v[228:229], off
	v_lshl_add_u64 v[228:229], v[250:251], 0, s[6:7]
	s_mov_b32 m0, s41
	s_nop 0
	global_load_lds_dwordx4 v[228:229], off
	v_lshl_add_u64 v[228:229], v[252:253], 0, s[6:7]
	s_mov_b32 m0, s42
	s_nop 0
	global_load_lds_dwordx4 v[228:229], off
	s_waitcnt vmcnt(8)
	s_waitcnt lgkmcnt(0)
	s_cmp_lg_u32 s98, 0
	s_setprio 1
	s_barrier
	s_cbranch_scc1 .Lgs_3
	v_mfma_f32_16x16x32_bf16 v[60:63], v[128:131], v[196:199], v[60:63]
	v_mfma_f32_16x16x32_bf16 v[56:59], v[140:143], v[196:199], v[56:59]
	v_mfma_f32_16x16x32_bf16 v[44:47], v[128:131], v[204:207], v[44:47]
	v_mfma_f32_16x16x32_bf16 v[40:43], v[140:143], v[204:207], v[40:43]
	v_mfma_f32_16x16x32_bf16 v[28:31], v[128:131], v[212:215], v[28:31]
	v_mfma_f32_16x16x32_bf16 v[24:27], v[140:143], v[212:215], v[24:27]
	v_mfma_f32_16x16x32_bf16 v[12:15], v[128:131], v[220:223], v[12:15]
	v_mfma_f32_16x16x32_bf16 v[8:11], v[140:143], v[220:223], v[8:11]
	v_mfma_f32_16x16x32_bf16 v[60:63], v[132:135], v[200:203], v[60:63]
	v_mfma_f32_16x16x32_bf16 v[56:59], v[176:179], v[200:203], v[56:59]
	v_mfma_f32_16x16x32_bf16 v[44:47], v[132:135], v[208:211], v[44:47]
	v_mfma_f32_16x16x32_bf16 v[40:43], v[176:179], v[208:211], v[40:43]
	v_mfma_f32_16x16x32_bf16 v[28:31], v[132:135], v[216:219], v[28:31]
	v_mfma_f32_16x16x32_bf16 v[24:27], v[176:179], v[216:219], v[24:27]
	v_mfma_f32_16x16x32_bf16 v[12:15], v[132:135], v[224:227], v[12:15]
	v_mfma_f32_16x16x32_bf16 v[8:11], v[176:179], v[224:227], v[8:11]
	s_setprio 0
	s_setprio 1
	v_mfma_f32_16x16x32_bf16 v[52:55], v[180:183], v[196:199], v[52:55]
	v_mfma_f32_16x16x32_bf16 v[48:51], v[188:191], v[196:199], v[48:51]
	v_mfma_f32_16x16x32_bf16 v[36:39], v[180:183], v[204:207], v[36:39]
	v_mfma_f32_16x16x32_bf16 v[32:35], v[188:191], v[204:207], v[32:35]
	v_mfma_f32_16x16x32_bf16 v[20:23], v[180:183], v[212:215], v[20:23]
	v_mfma_f32_16x16x32_bf16 v[16:19], v[188:191], v[212:215], v[16:19]
	v_mfma_f32_16x16x32_bf16 v[4:7], v[180:183], v[220:223], v[4:7]
	v_mfma_f32_16x16x32_bf16 v[0:3], v[188:191], v[220:223], v[0:3]
	v_mfma_f32_16x16x32_bf16 v[52:55], v[184:187], v[200:203], v[52:55]
	v_mfma_f32_16x16x32_bf16 v[48:51], v[192:195], v[200:203], v[48:51]
	v_mfma_f32_16x16x32_bf16 v[36:39], v[184:187], v[208:211], v[36:39]
	v_mfma_f32_16x16x32_bf16 v[32:35], v[192:195], v[208:211], v[32:35]
	v_mfma_f32_16x16x32_bf16 v[20:23], v[184:187], v[216:219], v[20:23]
	v_mfma_f32_16x16x32_bf16 v[16:19], v[192:195], v[216:219], v[16:19]
	v_mfma_f32_16x16x32_bf16 v[4:7], v[184:187], v[224:227], v[4:7]
	v_mfma_f32_16x16x32_bf16 v[0:3], v[192:195], v[224:227], v[0:3]
.Lgs_3:
	s_barrier
	s_setprio 0
	s_add_i32 s81, s81, 2
	s_add_u32 s0, s0, 0x100
	s_addc_u32 s1, s1, 0
	s_add_u32 s59, s59, 0x100
	s_addc_u32 s80, s80, 0
	s_cmp_gt_u32 s81, 13
	s_cbranch_scc1 .Lpeel_done_g2
; #define PG8_STAGE(bufoff, gbase, voff) do { _Pragma("unroll") for (int _i = 0; _i < 2; ++_i) \
;         __builtin_amdgcn_global_load_lds((const unsigned*)((const char*)(gbase) + (voff)[_i]), (PG8_LAS unsigned*)(lds + (bufoff) + ldsw + _i * 8192), 16, 0, 0); } while (0)
; #define PG8_LDA(dst, b, h) do { _Pragma("unroll") for (int m = 0; m < 4; ++m) _Pragma("unroll") for (int k = 0; k < 2; ++k) dst[m][k] = *(const PG8_LAS bf16x8*)(lds + PG8_SA(b, h) + aoff + m * 2048 + k * 1024); } while (0)
; #define PG8_LDB(dst, b, h) do { _Pragma("unroll") for (int n = 0; n < 2; ++n) _Pragma("unroll") for (int k = 0; k < 2; ++k) dst[n][k] = *(const PG8_LAS bf16x8*)(lds + PG8_SB(b, h) + boff + n * 2048 + k * 1024); } while (0)
; #define PG8_MMA(ai, bj, At, Bt) do { __builtin_amdgcn_s_setprio(1); _Pragma("unroll") for (int m = 0; m < 4; ++m) _Pragma("unroll") for (int n = 0; n < 2; ++n) _Pragma("unroll") for (int k = 0; k < 2; ++k) \
;         acc[ai][bj][m][n] = __builtin_amdgcn_mfma_f32_16x16x32_bf16(Bt[n][k], At[m][k], acc[ai][bj][m][n], 0, 0, 0); __builtin_amdgcn_s_setprio(0); } while (0)
; #define PG8_WAIT_V(n) asm volatile("s_waitcnt vmcnt(" #n ")" ::: "memory")
; #define PG8_WAIT_L(n) asm volatile("s_waitcnt lgkmcnt(" #n ")" ::: "memory")
; #define PG8_BAR __builtin_amdgcn_s_barrier()
; #define PG8_SCHED __builtin_amdgcn_sched_barrier(0)
; template <class Epi, class Sched, bool ALIGN_EPI = false, bool SP2 = false>
; __device__ __forceinline__ void gemm_phase(PG8_LAS unsigned char* lds, const Gemm g, const Sched& S, const Epi& E) {
;     ...
;             const char* a2 = last ? nA : cA + (size_t)(t + 2) * kstep; const char* b2 = last ? nB : cB + (size_t)(t + 2) * kstep;
;             const char* a3 = a2 + kstep; const char* b3 = b2 + kstep;
;             if (last && has_next) S.a_ready(nxt);
;             if constexpr (SP2) {
;             PG8_LDB(B0, 0, 0); PG8_LDB(B1, 0, 1); PG8_SCHED; PG8_LDA(At, 0, 0); PG8_STAGE(PG8_SA(1, 1), a1 + hstep, voffA);
;             PG8_WAIT_V(8); PG8_WAIT_L(0); PG8_BAR; PG8_MMA(0, 0, At, B0); PG8_MMA(0, 1, At, B1); PG8_BAR; PG8_SCHED;
;             PG8_LDA(At, 0, 1); PG8_STAGE(PG8_SB(0, 0), b2, voffB); PG8_STAGE(PG8_SB(0, 1), b2 + hstep, voffB); PG8_STAGE(PG8_SA(0, 0), a2, voffA);
;             PG8_WAIT_V(8); PG8_WAIT_L(0); PG8_BAR; PG8_MMA(1, 0, At, B0); PG8_MMA(1, 1, At, B1); PG8_BAR; PG8_SCHED;
.LBB0_464:
	ds_read_b128 v[128:131], v149
	ds_read_b128 v[132:135], v149 offset:1024
	ds_read_b128 v[140:143], v149 offset:2048
	ds_read_b128 v[176:179], v149 offset:3072
	ds_read_b128 v[180:183], v150
	ds_read_b128 v[184:187], v150 offset:1024
	ds_read_b128 v[188:191], v150 offset:2048
	ds_read_b128 v[192:195], v150 offset:3072
	s_add_u32 s30, s0, 0xfffc0080
	s_addc_u32 s31, s1, -1
	s_cmp_eq_u32 s81, 12
	s_cselect_b32 s35, s13, s31
	s_cselect_b32 s34, s21, s30
	s_cselect_b32 s31, s19, s80
	s_cselect_b32 s30, s58, s59
	v_lshl_add_u64 v[228:229], s[0:1], 0, v[136:137]
	s_add_i32 m0, s29, 0xc000
	ds_read_b128 v[196:199], v151
	ds_read_b128 v[200:203], v151 offset:1024
	ds_read_b128 v[204:207], v151 offset:2048
	ds_read_b128 v[208:211], v151 offset:3072
	ds_read_b128 v[212:215], v151 offset:4096
	ds_read_b128 v[216:219], v151 offset:5120
	ds_read_b128 v[220:223], v151 offset:6144
	ds_read_b128 v[224:227], v151 offset:7168
	global_load_lds_dwordx4 v[228:229], off
	v_lshl_add_u64 v[228:229], s[0:1], 0, v[138:139]
	s_add_i32 m0, s29, 0xe000
	s_nop 0
	global_load_lds_dwordx4 v[228:229], off
	s_waitcnt vmcnt(8)
	s_waitcnt lgkmcnt(0)
	s_cmp_lg_u32 s98, 0
	s_setprio 1
	s_barrier
	s_cbranch_scc1 .Lgs_4
	v_mfma_f32_16x16x32_bf16 v[124:127], v[128:131], v[196:199], v[124:127]
	v_mfma_f32_16x16x32_bf16 v[120:123], v[140:143], v[196:199], v[120:123]
	v_mfma_f32_16x16x32_bf16 v[108:111], v[128:131], v[204:207], v[108:111]
	v_mfma_f32_16x16x32_bf16 v[104:107], v[140:143], v[204:207], v[104:107]
	v_mfma_f32_16x16x32_bf16 v[92:95], v[128:131], v[212:215], v[92:95]
	v_mfma_f32_16x16x32_bf16 v[88:91], v[140:143], v[212:215], v[88:91]
	v_mfma_f32_16x16x32_bf16 v[76:79], v[128:131], v[220:223], v[76:79]
	v_mfma_f32_16x16x32_bf16 v[72:75], v[140:143], v[220:223], v[72:75]
	v_mfma_f32_16x16x32_bf16 v[124:127], v[132:135], v[200:203], v[124:127]
	v_mfma_f32_16x16x32_bf16 v[120:123], v[176:179], v[200:203], v[120:123]
	v_mfma_f32_16x16x32_bf16 v[108:111], v[132:135], v[208:211], v[108:111]
	v_mfma_f32_16x16x32_bf16 v[104:107], v[176:179], v[208:211], v[104:107]
	v_mfma_f32_16x16x32_bf16 v[92:95], v[132:135], v[216:219], v[92:95]
	v_mfma_f32_16x16x32_bf16 v[88:91], v[176:179], v[216:219], v[88:91]
	v_mfma_f32_16x16x32_bf16 v[76:79], v[132:135], v[224:227], v[76:79]
	v_mfma_f32_16x16x32_bf16 v[72:75], v[176:179], v[224:227], v[72:75]
	s_setprio 0
	s_setprio 1
	v_mfma_f32_16x16x32_bf16 v[116:119], v[180:183], v[196:199], v[116:119]
	v_mfma_f32_16x16x32_bf16 v[112:115], v[188:191], v[196:199], v[112:115]
	v_mfma_f32_16x16x32_bf16 v[100:103], v[180:183], v[204:207], v[100:103]
	v_mfma_f32_16x16x32_bf16 v[96:99], v[188:191], v[204:207], v[96:99]
	v_mfma_f32_16x16x32_bf16 v[84:87], v[180:183], v[212:215], v[84:87]
	v_mfma_f32_16x16x32_bf16 v[80:83], v[188:191], v[212:215], v[80:83]
	v_mfma_f32_16x16x32_bf16 v[68:71], v[180:183], v[220:223], v[68:71]
	v_mfma_f32_16x16x32_bf16 v[64:67], v[188:191], v[220:223], v[64:67]
	v_mfma_f32_16x16x32_bf16 v[116:119], v[184:187], v[200:203], v[116:119]
	v_mfma_f32_16x16x32_bf16 v[112:115], v[192:195], v[200:203], v[112:115]
	v_mfma_f32_16x16x32_bf16 v[100:103], v[184:187], v[208:211], v[100:103]
	v_mfma_f32_16x16x32_bf16 v[96:99], v[192:195], v[208:211], v[96:99]
	v_mfma_f32_16x16x32_bf16 v[84:87], v[184:187], v[216:219], v[84:87]
	v_mfma_f32_16x16x32_bf16 v[80:83], v[192:195], v[216:219], v[80:83]
	v_mfma_f32_16x16x32_bf16 v[68:71], v[184:187], v[224:227], v[68:71]
	v_mfma_f32_16x16x32_bf16 v[64:67], v[192:195], v[224:227], v[64:67]
.Lgs_4:
	s_barrier
	s_setprio 0
	s_add_i32 s82, s46, s3
	v_lshl_add_u64 v[228:229], s[30:31], 0, v[158:159]
	s_mov_b32 m0, s82
	ds_read_b128 v[196:199], v151 offset:16384
	ds_read_b128 v[200:203], v151 offset:17408
	ds_read_b128 v[204:207], v151 offset:18432
	ds_read_b128 v[208:211], v151 offset:19456
	ds_read_b128 v[212:215], v151 offset:20480
	ds_read_b128 v[216:219], v151 offset:21504
	ds_read_b128 v[220:223], v151 offset:22528
	ds_read_b128 v[224:227], v151 offset:23552
	global_load_lds_dwordx4 v[228:229], off
	s_add_i32 m0, s82, 0x2000
	s_add_u32 s82, s30, 0x40000
	v_lshl_add_u64 v[248:249], s[30:31], 0, v[162:163]
	s_addc_u32 s83, s31, 0
	s_add_i32 s84, s47, s3
	global_load_lds_dwordx4 v[248:249], off
	v_lshl_add_u64 v[250:251], s[82:83], 0, v[158:159]
	s_mov_b32 m0, s84
	v_lshl_add_u64 v[252:253], s[34:35], 0, v[160:161]
	global_load_lds_dwordx4 v[250:251], off
	v_lshl_add_u64 v[250:251], s[82:83], 0, v[162:163]
	s_add_i32 m0, s84, 0x2000
	s_nop 0
	global_load_lds_dwordx4 v[250:251], off
	v_lshl_add_u64 v[250:251], s[34:35], 0, v[156:157]
	s_mov_b32 m0, s29
	s_nop 0
	global_load_lds_dwordx4 v[250:251], off
	s_mov_b32 m0, s37
	s_nop 0
	global_load_lds_dwordx4 v[252:253], off
	s_waitcnt vmcnt(8)
	s_waitcnt lgkmcnt(0)
	s_cmp_lg_u32 s98, 0
	s_setprio 1
	s_barrier
	s_cbranch_scc1 .Lgs_5
	v_mfma_f32_16x16x32_bf16 v[60:63], v[128:131], v[196:199], v[60:63]
	v_mfma_f32_16x16x32_bf16 v[56:59], v[140:143], v[196:199], v[56:59]
	v_mfma_f32_16x16x32_bf16 v[44:47], v[128:131], v[204:207], v[44:47]
	v_mfma_f32_16x16x32_bf16 v[40:43], v[140:143], v[204:207], v[40:43]
	v_mfma_f32_16x16x32_bf16 v[28:31], v[128:131], v[212:215], v[28:31]
	v_mfma_f32_16x16x32_bf16 v[24:27], v[140:143], v[212:215], v[24:27]
	v_mfma_f32_16x16x32_bf16 v[12:15], v[128:131], v[220:223], v[12:15]
	v_mfma_f32_16x16x32_bf16 v[8:11], v[140:143], v[220:223], v[8:11]
	v_mfma_f32_16x16x32_bf16 v[60:63], v[132:135], v[200:203], v[60:63]
	v_mfma_f32_16x16x32_bf16 v[56:59], v[176:179], v[200:203], v[56:59]
	v_mfma_f32_16x16x32_bf16 v[44:47], v[132:135], v[208:211], v[44:47]
	v_mfma_f32_16x16x32_bf16 v[40:43], v[176:179], v[208:211], v[40:43]
	v_mfma_f32_16x16x32_bf16 v[28:31], v[132:135], v[216:219], v[28:31]
	v_mfma_f32_16x16x32_bf16 v[24:27], v[176:179], v[216:219], v[24:27]
	v_mfma_f32_16x16x32_bf16 v[12:15], v[132:135], v[224:227], v[12:15]
	v_mfma_f32_16x16x32_bf16 v[8:11], v[176:179], v[224:227], v[8:11]
	s_setprio 0
	s_setprio 1
	v_mfma_f32_16x16x32_bf16 v[52:55], v[180:183], v[196:199], v[52:55]
	v_mfma_f32_16x16x32_bf16 v[48:51], v[188:191], v[196:199], v[48:51]
	v_mfma_f32_16x16x32_bf16 v[36:39], v[180:183], v[204:207], v[36:39]
	v_mfma_f32_16x16x32_bf16 v[32:35], v[188:191], v[204:207], v[32:35]
	v_mfma_f32_16x16x32_bf16 v[20:23], v[180:183], v[212:215], v[20:23]
	v_mfma_f32_16x16x32_bf16 v[16:19], v[188:191], v[212:215], v[16:19]
	v_mfma_f32_16x16x32_bf16 v[4:7], v[180:183], v[220:223], v[4:7]
	v_mfma_f32_16x16x32_bf16 v[0:3], v[188:191], v[220:223], v[0:3]
	v_mfma_f32_16x16x32_bf16 v[52:55], v[184:187], v[200:203], v[52:55]
	v_mfma_f32_16x16x32_bf16 v[48:51], v[192:195], v[200:203], v[48:51]
	v_mfma_f32_16x16x32_bf16 v[36:39], v[184:187], v[208:211], v[36:39]
	v_mfma_f32_16x16x32_bf16 v[32:35], v[192:195], v[208:211], v[32:35]
	v_mfma_f32_16x16x32_bf16 v[20:23], v[184:187], v[216:219], v[20:23]
	v_mfma_f32_16x16x32_bf16 v[16:19], v[192:195], v[216:219], v[16:19]
	v_mfma_f32_16x16x32_bf16 v[4:7], v[184:187], v[224:227], v[4:7]
	v_mfma_f32_16x16x32_bf16 v[0:3], v[192:195], v[224:227], v[0:3]

; #define PG8_MMA(ai, bj, At, Bt) do { __builtin_amdgcn_s_setprio(1); _Pragma("unroll") for (int m = 0; m < 4; ++m) _Pragma("unroll") for (int n = 0; n < 2; ++n) _Pragma("unroll") for (int k = 0; k < 2; ++k) \
;         acc[ai][bj][m][n] = __builtin_amdgcn_mfma_f32_16x16x32_bf16(Bt[n][k], At[m][k], acc[ai][bj][m][n], 0, 0, 0); __builtin_amdgcn_s_setprio(0); } while (0)
; #define PG8_WAIT_V(n) asm volatile("s_waitcnt vmcnt(" #n ")" ::: "memory")
; #define PG8_WAIT_L(n) asm volatile("s_waitcnt lgkmcnt(" #n ")" ::: "memory")
; #define PG8_BAR __builtin_amdgcn_s_barrier()
; #define PG8_SCHED __builtin_amdgcn_sched_barrier(0)
; template <class Epi, class Sched, bool ALIGN_EPI = false, bool SP2 = false>
; __device__ __forceinline__ void gemm_phase(PG8_LAS unsigned char* lds, const Gemm g, const Sched& S, const Epi& E) {
;     ...
;         for (int t = 0; t < nt; t += 2) {
;             const bool last = (t == nt - 2);
;             const char* a1 = cA + (size_t)(t + 1) * kstep;
;             const char* a2 = last ? nA : cA + (size_t)(t + 2) * kstep; const char* b2 = last ? nB : cB + (size_t)(t + 2) * kstep;
;     ...
;             PG8_WAIT_V(8); PG8_WAIT_L(0); PG8_BAR; PG8_MMA(1, 0, At, B0); PG8_MMA(1, 1, At, B1); PG8_BAR; PG8_SCHED;
.Lgs_7:
	s_barrier
	s_setprio 0
	s_add_i32 s81, s81, 2
	s_add_u32 s0, s0, 0x100
	s_addc_u32 s1, s1, 0
	s_add_u32 s59, s59, 0x100
	s_addc_u32 s80, s80, 0
	s_cmp_gt_u32 s81, 13
	s_cbranch_scc0 .LBB0_464
